# attention: waves 0-3 (older half) run the staggered loop with the static priority raise instead of waves 4-7
# baseline (speedup 1.0000x reference)
; #define LAS __attribute__((address_space(3)))
; __device__ __forceinline__ void attn_phase(const Ctx& c, const Params& p, int o, int first, int cidx) {
;     ...
;         f32x16 o0 = {}, o1 = {}; float mrun = -INFINITY, lrun = 0.f;
;         const int ntile = 4 * (qblk + 1);
;         const bf16_t* kg = KH + (size_t)(b * T_) * 768 + h * 96; const bf16_t* vg = VT + (size_t)bh * 64 * T_;
;         u32x4 rk0, rk1 = {}, rv;
;         rk0 = *(const u32x4*)(kg + (size_t)k0row * 768 + 8 * k0ch); if (k1on) rk1 = *(const u32x4*)(kg + (size_t)k1row * 768 + 8 * k1ch); rv = *(const u32x4*)(vg + (size_t)vrow * T_ + 8 * vch);
;         *(LAS u32x4*)(sK + k0row * 104 + 8 * k0ch) = rk0; if (k1on) *(LAS u32x4*)(sK + k1row * 104 + 8 * k1ch) = rk1; *(LAS u32x4*)(sVt + vrow * 72 + 8 * vch) = rv;
;         __syncthreads();
;         for (int kt = 0; kt < ntile; ++kt) { const int kv0 = kt * 64; const int buf = kt & 1;
.LBB0_117:
	s_or_b64 exec, exec, s[18:19]
	s_lshl_b32 s11, s11, 20
	s_and_b32 s42, s11, 0x1f00000
	v_lshl_add_u64 v[118:119], v[114:115], 0, s[42:43]
	global_load_dwordx4 v[98:101], v[118:119], off
	s_waitcnt vmcnt(0) lgkmcnt(0)
	ds_write_b128 v126, v[90:93]
	s_and_saveexec_b64 s[18:19], s[6:7]
	ds_write_b128 v134, v[94:97]
	s_or_b64 exec, exec, s[18:19]
	v_mov_b32_e32 v14, v0
	v_mov_b32_e32 v15, v0
	v_mov_b32_e32 v1, v0
	v_mov_b32_e32 v2, v0
	v_mov_b32_e32 v3, v0
	v_mov_b32_e32 v4, v0
	v_mov_b32_e32 v5, v0
	v_mov_b32_e32 v6, v0
	v_mov_b32_e32 v7, v0
	v_mov_b32_e32 v8, v0
	v_mov_b32_e32 v9, v0
	v_mov_b32_e32 v10, v0
	v_mov_b32_e32 v11, v0
	v_mov_b32_e32 v12, v0
	v_mov_b32_e32 v13, v0
	v_mov_b64_e32 v[32:33], v[14:15]
	s_lshl_b32 s10, s10, 2
	s_mov_b32 s42, 0
	v_mov_b64_e32 v[30:31], v[12:13]
	v_mov_b64_e32 v[28:29], v[10:11]
	v_mov_b64_e32 v[26:27], v[8:9]
	v_mov_b64_e32 v[24:25], v[6:7]
	v_mov_b64_e32 v[22:23], v[4:5]
	v_mov_b64_e32 v[20:21], v[2:3]
	v_mov_b64_e32 v[18:19], v[0:1]
	v_mov_b64_e32 v[16:17], v[14:15]
	v_ashrrev_i32_e32 v117, 31, v116
	s_sub_i32 s27, 0x80, s10
	v_lshl_add_u64 v[120:121], v[106:107], 1, s[2:3]
	v_lshl_add_u64 v[122:123], v[110:111], 1, s[2:3]
	s_addk_i32 s29, 0x1f1f
	v_or_b32_e32 v135, s26, v124
	v_mov_b32_e32 v136, 0
	v_mov_b32_e32 v137, 0xff800000
	v_mov_b64_e32 v[14:15], v[12:13]
	v_mov_b64_e32 v[12:13], v[10:11]
	v_mov_b64_e32 v[10:11], v[8:9]
	v_mov_b64_e32 v[8:9], v[6:7]
	v_mov_b64_e32 v[6:7], v[4:5]
	v_mov_b64_e32 v[4:5], v[2:3]
	v_mov_b64_e32 v[2:3], v[0:1]
	s_mov_b32 s10, s42
	ds_write_b64 v251, v[98:99] offset:26624
	ds_write_b64 v252, v[100:101] offset:26624
	s_waitcnt lgkmcnt(0)
	s_barrier
	v_readlane_b32 s11, v255, 5
	s_cmp_lt_u32 s11, 4
	s_cbranch_scc1 .Lsb_loop
